# stack: NSA early-tile mirrored map + window tiles 0,1 prefetch + radix select ballot trim and early exit
# speedup vs baseline: 1.0337x; 1.0337x over previous
.LBB0_1029:
	s_or_b64 exec, exec, s[0:1]
	s_waitcnt lgkmcnt(0)
	s_barrier
	ds_read2st64_b32 v[0:1], v173 offset1:1
	v_add_u32_e32 v7, 0xf0, v174
	ds_read_b64 v[2:3], v161
	ds_read_b64 v[8:9], v162
	ds_read_b64 v[10:11], v163
	ds_read_b64 v[12:13], v164
	ds_read2st64_b32 v[14:15], v174 offset1:1
	ds_read2st64_b32 v[16:17], v174 offset0:33 offset1:34
	ds_read2st64_b32 v[18:19], v174 offset0:66 offset1:67
	ds_read2st64_b32 v[20:21], v174 offset0:99 offset1:100
	ds_read2st64_b32 v[22:23], v7 offset0:30 offset1:31
	ds_read2st64_b32 v[24:25], v7 offset0:63 offset1:64
	ds_read2st64_b32 v[26:27], v7 offset0:96 offset1:97
	ds_read2st64_b32 v[28:29], v7 offset0:129 offset1:130
	ds_read_b64 v[30:31], v165
	ds_read_b64 v[32:33], v166
	ds_read_b64 v[34:35], v167
	ds_read_b64 v[36:37], v168
	ds_read2st64_b32 v[38:39], v7 offset0:162 offset1:163
	ds_read2st64_b32 v[40:41], v7 offset0:195 offset1:196
	ds_read2st64_b32 v[42:43], v7 offset0:228 offset1:229
	ds_read2st64_b32 v[44:45], v174 offset0:132 offset1:133
	ds_read2st64_b32 v[46:47], v174 offset0:165 offset1:166
	ds_read2st64_b32 v[80:81], v174 offset0:198 offset1:199
	ds_read2st64_b32 v[82:83], v174 offset0:231 offset1:232
	s_ashr_i32 s76, s75, 2
	v_cmp_eq_u32_e64 s[0:1], s76, v128
	s_waitcnt lgkmcnt(14)
	v_mov_b32_e32 v84, v1
	v_mov_b32_e32 v85, v0
	v_pk_fma_f32 v[0:1], v[2:3], v[84:85], 0 op_sel_hi:[0,1,0]
	v_mov_b32_e32 v84, v23
	v_mov_b32_e32 v85, v22
	v_pk_fma_f32 v[0:1], v[8:9], v[84:85], v[0:1] op_sel_hi:[0,1,1]
	s_waitcnt lgkmcnt(13)
	v_mov_b32_e32 v22, v25
	v_mov_b32_e32 v23, v24
	v_pk_fma_f32 v[0:1], v[10:11], v[22:23], v[0:1] op_sel_hi:[0,1,1]
	s_waitcnt lgkmcnt(12)
	v_mov_b32_e32 v22, v27
	v_mov_b32_e32 v23, v26
	v_pk_fma_f32 v[0:1], v[12:13], v[22:23], v[0:1] op_sel_hi:[0,1,1]
	s_waitcnt lgkmcnt(11)
	v_mov_b32_e32 v22, v29
	v_mov_b32_e32 v23, v28
	s_waitcnt lgkmcnt(10)
	v_pk_fma_f32 v[0:1], v[30:31], v[22:23], v[0:1] op_sel_hi:[0,1,1]
	s_waitcnt lgkmcnt(6)
	v_mov_b32_e32 v22, v39
	v_mov_b32_e32 v23, v38
	v_pk_fma_f32 v[0:1], v[32:33], v[22:23], v[0:1] op_sel_hi:[0,1,1]
	s_waitcnt lgkmcnt(5)
	v_mov_b32_e32 v22, v41
	v_mov_b32_e32 v23, v40
	v_pk_fma_f32 v[0:1], v[34:35], v[22:23], v[0:1] op_sel_hi:[0,1,1]
	s_waitcnt lgkmcnt(4)
	v_mov_b32_e32 v22, v43
	v_mov_b32_e32 v23, v42
	v_pk_fma_f32 v[0:1], v[36:37], v[22:23], v[0:1] op_sel_hi:[0,1,1]
	v_mov_b32_e32 v22, v15
	v_mov_b32_e32 v23, v14
	v_pk_fma_f32 v[2:3], v[2:3], v[22:23], 0 op_sel:[1,0,0] op_sel_hi:[1,1,0]
	v_mov_b32_e32 v14, v17
	v_mov_b32_e32 v15, v16
	v_pk_fma_f32 v[2:3], v[8:9], v[14:15], v[2:3] op_sel:[1,0,0]
	v_mov_b32_e32 v8, v19
	v_mov_b32_e32 v9, v18
	v_pk_fma_f32 v[2:3], v[10:11], v[8:9], v[2:3] op_sel:[1,0,0]
	v_mov_b32_e32 v8, v21
	v_mov_b32_e32 v9, v20
	v_pk_fma_f32 v[2:3], v[12:13], v[8:9], v[2:3] op_sel:[1,0,0]
	s_waitcnt lgkmcnt(3)
	v_mov_b32_e32 v8, v45
	v_mov_b32_e32 v9, v44
	v_pk_fma_f32 v[2:3], v[30:31], v[8:9], v[2:3] op_sel:[1,0,0]
	s_waitcnt lgkmcnt(2)
	v_mov_b32_e32 v8, v47
	v_mov_b32_e32 v9, v46
	s_add_i32 s24, s76, 0xffffffbf
	s_add_i32 s22, s76, -1
	v_pk_fma_f32 v[2:3], v[32:33], v[8:9], v[2:3] op_sel:[1,0,0]
	s_waitcnt lgkmcnt(1)
	v_mov_b32_e32 v8, v81
	v_mov_b32_e32 v9, v80
	s_or_b64 s[26:27], s[6:7], s[0:1]
	v_cmp_eq_u32_e64 s[0:1], s76, v156
	v_pk_fma_f32 v[2:3], v[34:35], v[8:9], v[2:3] op_sel:[1,0,0]
	s_waitcnt lgkmcnt(0)
	v_mov_b32_e32 v8, v83
	v_mov_b32_e32 v9, v82
	v_cmp_eq_u32_e64 s[22:23], s22, v127
	v_cmp_eq_u32_e64 s[24:25], s24, v128
	v_pk_fma_f32 v[8:9], v[36:37], v[8:9], v[2:3] op_sel:[1,0,0]
	s_or_b64 s[22:23], s[26:27], s[22:23]
	s_or_b64 s[0:1], s[0:1], s[24:25]
	v_cmp_ge_i32_e64 s[20:21], s76, v128
	v_cmp_ge_i32_e32 vcc, s76, v156
	v_cndmask_b32_e64 v3, v1, v182, s[22:23]
	v_cndmask_b32_e64 v2, v0, v182, s[0:1]
	v_cndmask_b32_e64 v1, v9, v182, s[22:23]
	v_cndmask_b32_e64 v0, v8, v182, s[0:1]
	s_mov_b32 s77, 30
	s_mov_b32 s31, 0
	s_mov_b32 s30, 0
	s_mov_b32 s98, 64
	s_mov_b32 s100, 64
.LBB0_1030:
	s_lshl_b32 s0, 1, s77
	s_or_b32 s78, s0, s31
	s_or_b32 s79, s0, s30
	v_cmp_le_u32_e64 s[0:1], s78, v3
	v_cmp_le_u32_e64 s[22:23], s78, v2
	v_cmp_le_u32_e64 s[24:25], s79, v1
	v_cmp_le_u32_e64 s[26:27], s79, v0
	s_and_b64 s[0:1], s[20:21], s[0:1]
	s_and_b64 s[22:23], vcc, s[22:23]
	s_and_b64 s[24:25], s[20:21], s[24:25]
	s_and_b64 s[26:27], vcc, s[26:27]
	s_bcnt1_i32_b64 s0, s[0:1]
	s_bcnt1_i32_b64 s1, s[22:23]
	s_bcnt1_i32_b64 s22, s[24:25]
	s_bcnt1_i32_b64 s23, s[26:27]
	s_add_i32 s1, s1, s0
	s_add_i32 s23, s23, s22
	s_cmp_gt_u32 s1, 15
	s_cselect_b32 s31, s78, s31
	s_cselect_b32 s98, s1, s98
	s_cmp_gt_u32 s23, 15
	s_cselect_b32 s30, s79, s30
	s_cselect_b32 s100, s23, s100
	s_add_i32 s0, s98, s100
	s_cmp_eq_u32 s0, 32
	s_cbranch_scc1 .Lradix_done
	s_add_i32 s77, s77, -1
	s_cmp_eq_u32 s77, -1
	s_cbranch_scc0 .LBB0_1030
.Lradix_done:
	v_cmp_eq_u32_e64 s[26:27], s31, v3
	v_cmp_eq_u32_e64 s[24:25], s31, v2
	s_and_b64 s[78:79], s[20:21], s[26:27]
	v_cmp_lt_u32_e64 s[0:1], s31, v3
	v_cmp_lt_u32_e64 s[22:23], s31, v2
	v_cndmask_b32_e64 v2, 0, 1, s[78:79]
	s_and_b64 s[80:81], vcc, s[24:25]
	v_cmp_ne_u32_e64 s[26:27], 0, v2
	v_cndmask_b32_e64 v2, 0, 1, s[80:81]
	s_and_b64 s[82:83], s[20:21], s[0:1]
	v_cmp_ne_u32_e64 s[24:25], 0, v2
	v_cndmask_b32_e64 v2, 0, 1, s[82:83]
	s_and_b64 s[22:23], vcc, s[22:23]
	v_cmp_ne_u32_e64 s[0:1], 0, v2
	v_cndmask_b32_e64 v2, 0, 1, s[22:23]
	s_bcnt1_i32_b64 s31, s[0:1]
	v_cmp_ne_u32_e64 s[0:1], 0, v2
	v_and_b32_e32 v3, s26, v126
	s_bcnt1_i32_b64 s0, s[0:1]
	v_and_b32_e32 v2, s27, v125
	v_bcnt_u32_b32 v3, v3, 0
	v_and_b32_e32 v7, s24, v126
	s_add_i32 s31, s31, s0
	v_bcnt_u32_b32 v2, v2, v3
	v_and_b32_e32 v3, s25, v125
	v_bcnt_u32_b32 v7, v7, 0
	s_sub_i32 s31, 16, s31
	s_bcnt1_i32_b64 s0, s[26:27]
	v_bcnt_u32_b32 v3, v3, v7
	v_add_u32_e32 v3, s0, v3
	v_cmp_gt_i32_e64 s[0:1], s31, v2
	s_and_b64 s[0:1], s[78:79], s[0:1]
	s_or_b64 s[0:1], s[82:83], s[0:1]
	v_cndmask_b32_e64 v2, 0, 1, s[0:1]
	v_cmp_gt_i32_e64 s[0:1], s31, v3
	s_and_b64 s[0:1], s[80:81], s[0:1]
	s_or_b64 s[0:1], s[22:23], s[0:1]
	v_cmp_ne_u32_e64 s[24:25], 0, v2
	v_cndmask_b32_e64 v2, 0, 1, s[0:1]
	v_cmp_ne_u32_e64 s[0:1], 0, v2
	s_and_saveexec_b64 s[22:23], s[6:7]
	v_mov_b32_e32 v8, s24
	v_mov_b32_e32 v9, s25
	v_mov_b32_e32 v10, s0
	v_mov_b32_e32 v11, s1
	ds_write_b128 v175, v[8:11]
	s_or_b64 exec, exec, s[22:23]
	v_cmp_eq_u32_e64 s[26:27], s30, v1
	v_cmp_lt_u32_e64 s[0:1], s30, v1
	v_cmp_lt_u32_e64 s[22:23], s30, v0
	v_cmp_eq_u32_e64 s[24:25], s30, v0
	s_and_b64 s[30:31], s[20:21], s[26:27]
	v_cndmask_b32_e64 v0, 0, 1, s[30:31]
	s_and_b64 s[78:79], vcc, s[24:25]
	v_cmp_ne_u32_e64 s[26:27], 0, v0
	v_cndmask_b32_e64 v0, 0, 1, s[78:79]
	s_and_b64 s[20:21], s[20:21], s[0:1]
	v_cmp_ne_u32_e64 s[24:25], 0, v0
	v_cndmask_b32_e64 v0, 0, 1, s[20:21]
	v_cmp_ne_u32_e64 s[0:1], 0, v0
	s_bcnt1_i32_b64 s77, s[0:1]
	s_and_b64 s[0:1], vcc, s[22:23]
	v_cndmask_b32_e64 v0, 0, 1, s[0:1]
	v_cmp_ne_u32_e32 vcc, 0, v0
	v_and_b32_e32 v1, s26, v126
	s_bcnt1_i32_b64 s22, vcc
	v_and_b32_e32 v0, s27, v125
	v_bcnt_u32_b32 v1, v1, 0
	v_and_b32_e32 v2, s24, v126
	s_add_i32 s77, s77, s22
	v_bcnt_u32_b32 v0, v0, v1
	v_and_b32_e32 v1, s25, v125
	v_bcnt_u32_b32 v2, v2, 0
	s_sub_i32 s77, 16, s77
	s_bcnt1_i32_b64 s22, s[26:27]
	v_bcnt_u32_b32 v1, v1, v2
	v_add_u32_e32 v1, s22, v1
	v_cmp_gt_i32_e32 vcc, s77, v0
	s_and_b64 s[22:23], s[30:31], vcc
	v_cmp_gt_i32_e32 vcc, s77, v1
	s_or_b64 s[20:21], s[20:21], s[22:23]
	s_and_b64 s[22:23], s[78:79], vcc
	v_cndmask_b32_e64 v0, 0, 1, s[20:21]
	s_or_b64 s[0:1], s[0:1], s[22:23]
	v_cmp_ne_u32_e64 s[20:21], 0, v0
	v_cndmask_b32_e64 v0, 0, 1, s[0:1]
	v_cmp_ne_u32_e32 vcc, 0, v0
	s_and_saveexec_b64 s[0:1], s[6:7]
	v_mov_b32_e32 v0, s20
	v_mov_b32_e32 v1, s21
	v_mov_b32_e32 v2, vcc_lo
	v_mov_b32_e32 v3, vcc_hi
	ds_write_b128 v176, v[0:3]
	s_or_b64 exec, exec, s[0:1]
	s_waitcnt lgkmcnt(0)
	s_barrier
	ds_read_b32 v0, v157
	v_xor_b32_e32 v1, 4, v180
	v_cmp_lt_i32_e32 vcc, v1, v6
	v_xor_b32_e32 v2, 8, v180
	s_nop 0
	v_cndmask_b32_e32 v1, v180, v1, vcc
	v_lshlrev_b32_e32 v1, 2, v1
	s_waitcnt lgkmcnt(0)
	ds_bpermute_b32 v1, v1, v0
	v_cmp_lt_i32_e32 vcc, v2, v6
	s_waitcnt lgkmcnt(0)
	v_or_b32_e32 v3, v0, v1
	v_cndmask_b32_e32 v2, v180, v2, vcc
	v_lshlrev_b32_e32 v2, 2, v2
	v_and_b32_e32 v7, v0, v1
	ds_bpermute_b32 v6, v2, v3
	ds_bpermute_b32 v2, v2, v7
	s_waitcnt lgkmcnt(1)
	v_or_b32_e32 v3, v3, v6
	s_waitcnt lgkmcnt(0)
	v_bitop3_b32 v0, v2, v0, v1 bitop3:0x80
	ds_bpermute_b32 v6, v4, v3
	ds_bpermute_b32 v1, v4, v0
	s_waitcnt lgkmcnt(1)
	v_or_b32_e32 v3, v3, v6
	s_waitcnt lgkmcnt(0)
	v_bitop3_b32 v2, v2, v1, v7 bitop3:0x80
	ds_bpermute_b32 v4, v5, v3
	ds_bpermute_b32 v2, v5, v2
	s_waitcnt lgkmcnt(1)
	v_or_b32_e32 v3, v3, v4
	s_waitcnt lgkmcnt(0)
	v_bitop3_b32 v0, v0, v2, v1 bitop3:0x80
	v_readlane_b32 s20, v3, 0
	v_readlane_b32 s21, v3, 1
	v_readlane_b32 s22, v3, 2
	v_readlane_b32 s23, v3, 3
	v_readlane_b32 s26, v0, 0
	v_readlane_b32 s27, v0, 1
	v_readlane_b32 s77, v0, 2
	v_readlane_b32 s78, v0, 3
	s_and_saveexec_b64 s[0:1], s[8:9]
	s_cbranch_execz .LBB0_1038
	v_mov_b32_e32 v0, s23
	v_mov_b32_e32 v1, s22
	v_cndmask_b32_e64 v0, v0, v1, s[14:15]
	v_mov_b32_e32 v1, s21
	v_cndmask_b32_e64 v0, v0, v1, s[12:13]
	v_mov_b32_e32 v1, s20
	v_cndmask_b32_e64 v0, v0, v1, s[10:11]
	v_and_b32_e32 v1, v0, v158
	v_cmp_ne_u32_e32 vcc, 0, v1
	s_and_b64 exec, exec, vcc
	s_cbranch_execz .LBB0_1038
	s_bcnt1_i32_b32 s24, s20
	v_mov_b32_e32 v1, s24
	s_bcnt1_i32_b32 s24, s21
	v_mov_b32_e32 v2, s24
	s_bcnt1_i32_b32 s24, s22
	v_cndmask_b32_e64 v1, v1, 0, s[10:11]
	v_cndmask_b32_e64 v2, 0, v2, s[16:17]
	v_mov_b32_e32 v3, s24
	v_and_b32_e32 v0, v0, v159
	v_cndmask_b32_e64 v3, 0, v3, s[18:19]
	v_bcnt_u32_b32 v0, v0, 0
	v_lshlrev_b32_e32 v1, 2, v1
	v_lshlrev_b32_e32 v2, 2, v2
	v_add3_u32 v1, s72, v1, v2
	v_lshlrev_b32_e32 v2, 2, v3
	v_lshlrev_b32_e32 v0, 2, v0
	v_add3_u32 v0, v1, v2, v0
	ds_write_b32 v0, v129
.LBB0_1038:
	s_or_b64 exec, exec, s[0:1]
	s_bcnt1_i32_b32 s0, s21
	s_bcnt1_i32_b32 s1, s22
	s_bcnt1_i32_b32 s21, s23
	s_lshl_b32 s22, s40, 25
	s_add_u32 s22, s36, s22
	s_addc_u32 s23, s37, 0
	s_bcnt1_i32_b32 s20, s20
	s_add_i32 s0, s0, s20
	s_add_i32 s79, s0, s1
	s_add_i32 s79, s79, s21
	s_lshl_b32 s0, s29, 7
	s_add_u32 s24, s22, s0
	v_sub_co_u32_e64 v32, s[0:1], s79, 1
	s_waitcnt lgkmcnt(0)
	s_barrier
	s_nop 0
	v_cndmask_b32_e64 v0, 0, -1, s[0:1]
	v_lshlrev_b32_e32 v0, 2, v0
	v_add_u32_e32 v0, s72, v0
	ds_read_b32 v0, v0
	s_addc_u32 s25, s23, 0
	s_lshl_b32 s0, s47, 20
	s_add_u32 s20, s55, s0
	s_addc_u32 s21, s56, 0
	s_waitcnt lgkmcnt(0)
	v_readfirstlane_b32 s0, v0
	s_lshl_b32 s0, s0, 6
	s_ashr_i32 s1, s0, 31
	s_lshl_b64 s[22:23], s[0:1], 12
	s_add_u32 s22, s24, s22
	s_addc_u32 s23, s25, s23
	s_lshl_b64 s[0:1], s[0:1], 1
	s_add_u32 s0, s20, s0
	s_addc_u32 s1, s21, s1
	s_cmp_lt_u32 s79, 2
	v_mov_b32_e32 v139, v123
	v_mov_b32_e32 v141, v123
	s_cselect_b64 vcc, -1, 0
	v_lshl_add_u64 v[0:1], s[22:23], 0, v[138:139]
	v_lshl_add_u64 v[2:3], s[0:1], 0, v[140:141]
	v_cndmask_b32_e32 v8, 1, v32, vcc
	v_lshl_add_u64 v[0:1], v[0:1], 0, v[122:123]
	v_lshl_add_u64 v[4:5], v[2:3], 0, v[122:123]
	v_lshlrev_b32_e32 v8, 2, v8
	global_load_dwordx4 v[0:3], v[0:1], off offset:2560
	s_nop 0
	global_load_dwordx4 v[4:7], v[4:5], off
	v_add_u32_e32 v8, s72, v8
	ds_read_b32 v8, v8
	v_readfirstlane_b32 s80, v32
	v_add_f32_e32 v137, v146, v146
	v_mul_f32_e32 v188, 0x40400000, v146
	v_mul_f32_e32 v189, 0x41800000, v146
	s_waitcnt lgkmcnt(0)
	v_readfirstlane_b32 s0, v8
	s_lshl_b32 s0, s0, 6
	s_ashr_i32 s1, s0, 31
	s_lshl_b64 s[22:23], s[0:1], 12
	s_add_u32 s22, s24, s22
	s_addc_u32 s23, s25, s23
	s_lshl_b64 s[0:1], s[0:1], 1
	s_add_u32 s0, s20, s0
	s_addc_u32 s1, s21, s1
	v_lshl_add_u64 v[8:9], s[22:23], 0, v[138:139]
	v_lshl_add_u64 v[10:11], s[0:1], 0, v[140:141]
	v_lshl_add_u64 v[8:9], v[8:9], 0, v[122:123]
	v_lshl_add_u64 v[12:13], v[10:11], 0, v[122:123]
	global_load_dwordx4 v[8:11], v[8:9], off offset:2560
	s_nop 0
	global_load_dwordx4 v[12:15], v[12:13], off
	s_cmp_lt_u32 s79, 3
	s_cselect_b64 s[0:1], -1, 0
	v_cndmask_b32_e64 v16, 2, v32, s[0:1]
	v_lshlrev_b32_e32 v16, 2, v16
	v_add_u32_e32 v16, s72, v16
	v_mul_f32_e32 v190, 0x42000000, v146
	v_mul_f32_e32 v191, 0x42400000, v146
	v_mul_f32_e32 v192, 0, v146
	s_waitcnt vmcnt(3)
	ds_write_b128 v151, v[0:3]
	s_waitcnt vmcnt(2)
	ds_write2_b64 v187, v[4:5], v[6:7] offset1:2
	s_waitcnt vmcnt(1)
	ds_write_b128 v151, v[8:11] offset:10240
	s_waitcnt vmcnt(0)
	ds_write2_b64 v186, v[12:13], v[14:15] offset1:2
	s_lshl_b32 s98, s47, 20
	s_add_u32 s98, s57, s98
	s_addc_u32 s99, s60, 0
	s_add_i32 s29, s74, 0xfffffe01
	s_andn2_b32 s29, s29, 63
	s_cmp_gt_i32 s75, 31
	s_cselect_b32 s29, s29, 0
	s_sub_i32 s30, s74, s29
	s_ashr_i32 s30, s30, 6
	v_mov_b32_e32 v4, v138
	v_mov_b32_e32 v5, 0
	v_mov_b32_e32 v6, v140
	v_mov_b32_e32 v7, 0
	s_min_i32 s22, s30, 0
	s_lshl_b32 s22, s22, 6
	s_add_i32 s22, s22, s29
	s_ashr_i32 s23, s22, 31
	s_lshl_b64 s[100:101], s[22:23], 12
	s_add_u32 s100, s24, s100
	s_addc_u32 s101, s25, s101
	s_lshl_b64 s[22:23], s[22:23], 1
	s_add_u32 s22, s98, s22
	s_addc_u32 s23, s99, s23
	v_lshl_add_u64 v[0:1], s[100:101], 0, v[4:5]
	v_lshl_add_u64 v[2:3], s[22:23], 0, v[6:7]
	v_lshl_add_u64 v[0:1], v[0:1], 0, v[122:123]
	v_lshl_add_u64 v[2:3], v[2:3], 0, v[122:123]
	global_load_dwordx4 v[240:243], v[0:1], off offset:3072
	global_load_dwordx4 v[244:247], v[2:3], off
	s_min_i32 s22, s30, 1
	s_lshl_b32 s22, s22, 6
	s_add_i32 s22, s22, s29
	s_ashr_i32 s23, s22, 31
	s_lshl_b64 s[100:101], s[22:23], 12
	s_add_u32 s100, s24, s100
	s_addc_u32 s101, s25, s101
	s_lshl_b64 s[22:23], s[22:23], 1
	s_add_u32 s22, s98, s22
	s_addc_u32 s23, s99, s23
	v_lshl_add_u64 v[0:1], s[100:101], 0, v[4:5]
	v_lshl_add_u64 v[2:3], s[22:23], 0, v[6:7]
	v_lshl_add_u64 v[0:1], v[0:1], 0, v[122:123]
	v_lshl_add_u64 v[2:3], v[2:3], 0, v[122:123]
	global_load_dwordx4 v[248:251], v[0:1], off offset:3072
	global_load_dwordx4 v[252:255], v[2:3], off
	ds_read_b32 v0, v16
	s_waitcnt lgkmcnt(0)
	v_readfirstlane_b32 s0, v0
	s_lshl_b32 s0, s0, 6
	s_ashr_i32 s1, s0, 31
	s_lshl_b64 s[22:23], s[0:1], 12
	s_add_u32 s22, s24, s22
	s_addc_u32 s23, s25, s23
	s_lshl_b64 s[0:1], s[0:1], 1
	s_add_u32 s0, s20, s0
	s_addc_u32 s1, s21, s1
	s_cmp_lt_u32 s79, 4
	v_lshl_add_u64 v[0:1], s[22:23], 0, v[138:139]
	v_lshl_add_u64 v[2:3], s[0:1], 0, v[140:141]
	s_cselect_b64 s[0:1], -1, 0
	v_lshl_add_u64 v[0:1], v[0:1], 0, v[122:123]
	v_cndmask_b32_e64 v4, 3, v32, s[0:1]
	v_lshl_add_u64 v[2:3], v[2:3], 0, v[122:123]
	global_load_dwordx4 v[20:23], v[0:1], off offset:2560
	global_load_dwordx4 v[16:19], v[2:3], off
	v_lshlrev_b32_e32 v0, 2, v4
	v_add_u32_e32 v0, s72, v0
	ds_read_b32 v0, v0
	s_waitcnt lgkmcnt(0)
	v_readfirstlane_b32 s0, v0
	s_lshl_b32 s0, s0, 6
	s_ashr_i32 s1, s0, 31
	s_lshl_b64 s[22:23], s[0:1], 12
	s_add_u32 s22, s24, s22
	s_addc_u32 s23, s25, s23
	s_lshl_b64 s[0:1], s[0:1], 1
	s_add_u32 s0, s20, s0
	v_lshl_add_u64 v[0:1], s[22:23], 0, v[138:139]
	s_addc_u32 s1, s21, s1
	v_lshl_add_u64 v[0:1], v[0:1], 0, v[122:123]
	v_lshl_add_u64 v[2:3], s[0:1], 0, v[140:141]
	v_lshl_add_u64 v[2:3], v[2:3], 0, v[122:123]
	global_load_dwordx4 v[28:31], v[0:1], off offset:2560
	global_load_dwordx4 v[24:27], v[2:3], off
	s_waitcnt lgkmcnt(0)
	s_barrier
	v_lshl_add_u64 v[0:1], s[24:25], 0, v[138:139]
	v_lshl_add_u64 v[120:121], v[0:1], 0, v[122:123]
	s_and_b64 vcc, exec, vcc
	s_cbranch_vccnz .LBB0_1050
	v_lshl_add_u64 v[0:1], s[20:21], 0, v[140:141]
	v_mov_b32_e32 v36, 0
	v_lshl_add_u64 v[148:149], v[0:1], 0, v[122:123]
	v_sub_u32_e32 v139, v144, v124
	v_mov_b32_e32 v32, v123
	v_mov_b32_e32 v33, v123
	v_mov_b32_e32 v34, v123
	v_mov_b32_e32 v35, v123
	s_mov_b32 s83, 5
	s_movk_i32 s81, 0x80
	s_mov_b32 s82, s72
	v_mov_b32_e32 v37, v36
	v_mov_b32_e32 v38, v36
	v_mov_b32_e32 v39, v36
	v_mov_b32_e32 v40, v36
	v_mov_b32_e32 v41, v36
	v_mov_b32_e32 v42, v36
	v_mov_b32_e32 v43, v36
	v_mov_b32_e32 v44, v36
	v_mov_b32_e32 v45, v36
	v_mov_b32_e32 v46, v36
	v_mov_b32_e32 v47, v36
	v_mov_b32_e32 v84, v36
	v_mov_b32_e32 v85, v36
	v_mov_b32_e32 v86, v36
	v_mov_b32_e32 v87, v36
